# ple-gate epilogue hand-written: 16 ple loads first, sigmoid in place with packed scale/+1, multiply as loads land
# baseline (speedup 1.0000x reference)
; __device__ __forceinline__ float sigmoidf_(float x) { return __builtin_amdgcn_rcpf(1.0f + __expf(-x)); }
; __device__ __forceinline__ f32x4 sig4(const f32x4 v) { return (f32x4){sigmoidf_(v[0]), sigmoidf_(v[1]), sigmoidf_(v[2]), sigmoidf_(v[3])}; }
;     __device__ __forceinline__ void ple_gate(f32x4 (&acc)[2][2][4][2], const GUnit& u, int wr, int wc, int fr, int fq) const {
;         const f16* ple = (const f16*)(ws + WS_PLE); const int grow0 = u.pm * 256 + wr * 64 + fr, gcol0 = u.pn * 256 + wc * 32 + 8 * fq;
;         u32x4 pw[2][4][2];
; #pragma unroll
;         for (int ai = 0; ai < 2; ++ai)
; #pragma unroll
;             for (int m = 0; m < 4; ++m)
; #pragma unroll
;                 for (int bj = 0; bj < 2; ++bj) pw[ai][m][bj] = *(const u32x4*)(ple + (size_t)(grow0 + ai * 128 + m * 16) * 1024 + gcol0 + bj * 128);
;         asm volatile("" ::: "memory");
; #pragma unroll
;         for (int ai = 0; ai < 2; ++ai)
; #pragma unroll
;             for (int m = 0; m < 4; ++m)
; #pragma unroll
;                 for (int bj = 0; bj < 2; ++bj) { f32x4 p0, p1; unpk8(pw[ai][m][bj], p0, p1); acc[ai][bj][m][0] = sig4(acc[ai][bj][m][0]) * p0; acc[ai][bj][m][1] = sig4(acc[ai][bj][m][1]) * p1; }
;     }
.LBB0_380:
	s_lshl_b32 s8, s37, 8
	s_add_i32 s8, s8, s48
	v_or_b32_e32 v132, s8, v185
	s_lshl_b32 s8, s34, 8
	v_readlane_b32 s9, v251, 28
	s_or_b32 s8, s8, s9
	v_lshl_add_u32 v134, v35, 3, s8
	v_readlane_b32 s8, v252, 3
	v_readlane_b32 s9, v252, 4
	v_ashrrev_i32_e32 v135, 31, v134
	v_ashrrev_i32_e32 v133, 31, v132
	s_mov_b32 s98, 0xbfb8aa3b
	v_lshl_add_u64 v[134:135], v[134:135], 1, s[8:9]
	v_lshlrev_b64 v[132:133], 11, v[132:133]
	v_lshl_add_u64 v[132:133], v[134:135], 0, v[132:133]
	global_load_dwordx4 v[136:139], v[132:133], off
	global_load_dwordx4 v[140:143], v[132:133], off offset:256
	v_add_co_u32_e32 v134, vcc, 0x8000, v132
	v_addc_co_u32_e32 v135, vcc, 0, v133, vcc
	global_load_dwordx4 v[144:147], v[134:135], off
	global_load_dwordx4 v[148:151], v[134:135], off offset:256
	v_add_co_u32_e32 v134, vcc, 0x10000, v132
	v_addc_co_u32_e32 v135, vcc, 0, v133, vcc
	global_load_dwordx4 v[152:155], v[134:135], off
	global_load_dwordx4 v[156:159], v[134:135], off offset:256
	v_add_co_u32_e32 v134, vcc, 0x18000, v132
	v_addc_co_u32_e32 v135, vcc, 0, v133, vcc
	global_load_dwordx4 v[160:163], v[134:135], off
	global_load_dwordx4 v[164:167], v[134:135], off offset:256
	v_add_co_u32_e32 v134, vcc, 0x40000, v132
	v_addc_co_u32_e32 v135, vcc, 0, v133, vcc
	global_load_dwordx4 v[168:171], v[134:135], off
	global_load_dwordx4 v[172:175], v[134:135], off offset:256
	v_add_co_u32_e32 v134, vcc, 0x48000, v132
	v_addc_co_u32_e32 v135, vcc, 0, v133, vcc
	global_load_dwordx4 v[176:179], v[134:135], off
	global_load_dwordx4 v[180:183], v[134:135], off offset:256
	v_add_co_u32_e32 v134, vcc, 0x50000, v132
	v_addc_co_u32_e32 v135, vcc, 0, v133, vcc
	global_load_dwordx4 v[190:193], v[134:135], off
	global_load_dwordx4 v[198:201], v[134:135], off offset:256
	v_add_co_u32_e32 v134, vcc, 0x58000, v132
	v_addc_co_u32_e32 v135, vcc, 0, v133, vcc
	global_load_dwordx4 v[204:207], v[134:135], off
	global_load_dwordx4 v[208:211], v[134:135], off offset:256
	v_pk_mul_f32 v[128:129], v[128:129], s[98:99] op_sel_hi:[1,0]
	v_pk_mul_f32 v[130:131], v[130:131], s[98:99] op_sel_hi:[1,0]
	v_pk_mul_f32 v[124:125], v[124:125], s[98:99] op_sel_hi:[1,0]
	v_pk_mul_f32 v[126:127], v[126:127], s[98:99] op_sel_hi:[1,0]
	v_exp_f32_e32 v128, v128
	v_exp_f32_e32 v124, v124
	v_exp_f32_e32 v129, v129
	v_exp_f32_e32 v125, v125
	v_exp_f32_e32 v130, v130
	v_exp_f32_e32 v126, v126
	v_exp_f32_e32 v131, v131
	v_exp_f32_e32 v127, v127
	v_pk_add_f32 v[128:129], v[128:129], 1.0 op_sel_hi:[1,0]
	v_pk_add_f32 v[130:131], v[130:131], 1.0 op_sel_hi:[1,0]
	v_pk_add_f32 v[124:125], v[124:125], 1.0 op_sel_hi:[1,0]
	v_pk_add_f32 v[126:127], v[126:127], 1.0 op_sel_hi:[1,0]
	v_rcp_f32_e32 v128, v128
	v_rcp_f32_e32 v124, v124
	v_rcp_f32_e32 v129, v129
	v_rcp_f32_e32 v125, v125
	v_rcp_f32_e32 v130, v130
	v_rcp_f32_e32 v126, v126
	v_rcp_f32_e32 v131, v131
	v_rcp_f32_e32 v127, v127
	v_pk_mul_f32 v[120:121], v[120:121], s[98:99] op_sel_hi:[1,0]
	v_pk_mul_f32 v[122:123], v[122:123], s[98:99] op_sel_hi:[1,0]
	v_pk_mul_f32 v[116:117], v[116:117], s[98:99] op_sel_hi:[1,0]
	v_pk_mul_f32 v[118:119], v[118:119], s[98:99] op_sel_hi:[1,0]
	v_exp_f32_e32 v120, v120
	v_exp_f32_e32 v116, v116
	v_exp_f32_e32 v121, v121
	v_exp_f32_e32 v117, v117
	v_exp_f32_e32 v122, v122
	v_exp_f32_e32 v118, v118
	v_exp_f32_e32 v123, v123
	v_exp_f32_e32 v119, v119
	v_pk_add_f32 v[120:121], v[120:121], 1.0 op_sel_hi:[1,0]
	v_pk_add_f32 v[122:123], v[122:123], 1.0 op_sel_hi:[1,0]
	v_pk_add_f32 v[116:117], v[116:117], 1.0 op_sel_hi:[1,0]
	v_pk_add_f32 v[118:119], v[118:119], 1.0 op_sel_hi:[1,0]
	v_rcp_f32_e32 v120, v120
	v_rcp_f32_e32 v116, v116
	v_rcp_f32_e32 v121, v121
	v_rcp_f32_e32 v117, v117
	v_rcp_f32_e32 v122, v122
	v_rcp_f32_e32 v118, v118
	v_rcp_f32_e32 v123, v123
	v_rcp_f32_e32 v119, v119
	v_pk_mul_f32 v[112:113], v[112:113], s[98:99] op_sel_hi:[1,0]
	v_pk_mul_f32 v[114:115], v[114:115], s[98:99] op_sel_hi:[1,0]
	v_pk_mul_f32 v[108:109], v[108:109], s[98:99] op_sel_hi:[1,0]
	v_pk_mul_f32 v[110:111], v[110:111], s[98:99] op_sel_hi:[1,0]
	v_exp_f32_e32 v112, v112
	v_exp_f32_e32 v108, v108
	v_exp_f32_e32 v113, v113
	v_exp_f32_e32 v109, v109
	v_exp_f32_e32 v114, v114
	v_exp_f32_e32 v110, v110
	v_exp_f32_e32 v115, v115
	v_exp_f32_e32 v111, v111
	v_pk_add_f32 v[112:113], v[112:113], 1.0 op_sel_hi:[1,0]
	v_pk_add_f32 v[114:115], v[114:115], 1.0 op_sel_hi:[1,0]
	v_pk_add_f32 v[108:109], v[108:109], 1.0 op_sel_hi:[1,0]
	v_pk_add_f32 v[110:111], v[110:111], 1.0 op_sel_hi:[1,0]
	v_rcp_f32_e32 v112, v112
	v_rcp_f32_e32 v108, v108
	v_rcp_f32_e32 v113, v113
	v_rcp_f32_e32 v109, v109
	v_rcp_f32_e32 v114, v114
	v_rcp_f32_e32 v110, v110
	v_rcp_f32_e32 v115, v115
	v_rcp_f32_e32 v111, v111
	v_pk_mul_f32 v[104:105], v[104:105], s[98:99] op_sel_hi:[1,0]
	v_pk_mul_f32 v[106:107], v[106:107], s[98:99] op_sel_hi:[1,0]
	v_pk_mul_f32 v[100:101], v[100:101], s[98:99] op_sel_hi:[1,0]
	v_pk_mul_f32 v[102:103], v[102:103], s[98:99] op_sel_hi:[1,0]
	v_exp_f32_e32 v104, v104
	v_exp_f32_e32 v100, v100
	v_exp_f32_e32 v105, v105
	v_exp_f32_e32 v101, v101
	v_exp_f32_e32 v106, v106
	v_exp_f32_e32 v102, v102
	v_exp_f32_e32 v107, v107
	v_exp_f32_e32 v103, v103
	v_pk_add_f32 v[104:105], v[104:105], 1.0 op_sel_hi:[1,0]
	v_pk_add_f32 v[106:107], v[106:107], 1.0 op_sel_hi:[1,0]
	v_pk_add_f32 v[100:101], v[100:101], 1.0 op_sel_hi:[1,0]
	v_pk_add_f32 v[102:103], v[102:103], 1.0 op_sel_hi:[1,0]
	v_rcp_f32_e32 v104, v104
	v_rcp_f32_e32 v100, v100
	v_rcp_f32_e32 v105, v105
	v_rcp_f32_e32 v101, v101
	v_rcp_f32_e32 v106, v106
	v_rcp_f32_e32 v102, v102
	v_rcp_f32_e32 v107, v107
	v_rcp_f32_e32 v103, v103
	v_pk_mul_f32 v[96:97], v[96:97], s[98:99] op_sel_hi:[1,0]
; __device__ __forceinline__ float sigmoidf_(float x) { return __builtin_amdgcn_rcpf(1.0f + __expf(-x)); }
; __device__ __forceinline__ f32x4 sig4(const f32x4 v) { return (f32x4){sigmoidf_(v[0]), sigmoidf_(v[1]), sigmoidf_(v[2]), sigmoidf_(v[3])}; }
;     __device__ __forceinline__ void ple_gate(f32x4 (&acc)[2][2][4][2], const GUnit& u, int wr, int wc, int fr, int fq) const {
;         const f16* ple = (const f16*)(ws + WS_PLE); const int grow0 = u.pm * 256 + wr * 64 + fr, gcol0 = u.pn * 256 + wc * 32 + 8 * fq;
;         u32x4 pw[2][4][2];
; #pragma unroll
;         for (int ai = 0; ai < 2; ++ai)
; #pragma unroll
;             for (int m = 0; m < 4; ++m)
; #pragma unroll
;                 for (int bj = 0; bj < 2; ++bj) pw[ai][m][bj] = *(const u32x4*)(ple + (size_t)(grow0 + ai * 128 + m * 16) * 1024 + gcol0 + bj * 128);
;         asm volatile("" ::: "memory");
; #pragma unroll
;         for (int ai = 0; ai < 2; ++ai)
; #pragma unroll
;             for (int m = 0; m < 4; ++m)
; #pragma unroll
;                 for (int bj = 0; bj < 2; ++bj) { f32x4 p0, p1; unpk8(pw[ai][m][bj], p0, p1); acc[ai][bj][m][0] = sig4(acc[ai][bj][m][0]) * p0; acc[ai][bj][m][1] = sig4(acc[ai][bj][m][1]) * p1; }
;     }
	v_pk_mul_f32 v[98:99], v[98:99], s[98:99] op_sel_hi:[1,0]
	v_pk_mul_f32 v[92:93], v[92:93], s[98:99] op_sel_hi:[1,0]
	v_pk_mul_f32 v[94:95], v[94:95], s[98:99] op_sel_hi:[1,0]
	v_exp_f32_e32 v96, v96
	v_exp_f32_e32 v92, v92
	v_exp_f32_e32 v97, v97
	v_exp_f32_e32 v93, v93
	v_exp_f32_e32 v98, v98
	v_exp_f32_e32 v94, v94
	v_exp_f32_e32 v99, v99
	v_exp_f32_e32 v95, v95
	v_pk_add_f32 v[96:97], v[96:97], 1.0 op_sel_hi:[1,0]
	v_pk_add_f32 v[98:99], v[98:99], 1.0 op_sel_hi:[1,0]
	v_pk_add_f32 v[92:93], v[92:93], 1.0 op_sel_hi:[1,0]
	v_pk_add_f32 v[94:95], v[94:95], 1.0 op_sel_hi:[1,0]
	v_rcp_f32_e32 v96, v96
	v_rcp_f32_e32 v92, v92
	v_rcp_f32_e32 v97, v97
	v_rcp_f32_e32 v93, v93
	v_rcp_f32_e32 v98, v98
	v_rcp_f32_e32 v94, v94
	v_rcp_f32_e32 v99, v99
	v_rcp_f32_e32 v95, v95
	v_pk_mul_f32 v[88:89], v[88:89], s[98:99] op_sel_hi:[1,0]
	v_pk_mul_f32 v[90:91], v[90:91], s[98:99] op_sel_hi:[1,0]
	v_pk_mul_f32 v[84:85], v[84:85], s[98:99] op_sel_hi:[1,0]
	v_pk_mul_f32 v[86:87], v[86:87], s[98:99] op_sel_hi:[1,0]
	v_exp_f32_e32 v88, v88
	v_exp_f32_e32 v84, v84
	v_exp_f32_e32 v89, v89
	v_exp_f32_e32 v85, v85
	v_exp_f32_e32 v90, v90
	v_exp_f32_e32 v86, v86
	v_exp_f32_e32 v91, v91
	v_exp_f32_e32 v87, v87
	v_pk_add_f32 v[88:89], v[88:89], 1.0 op_sel_hi:[1,0]
	v_pk_add_f32 v[90:91], v[90:91], 1.0 op_sel_hi:[1,0]
	v_pk_add_f32 v[84:85], v[84:85], 1.0 op_sel_hi:[1,0]
	v_pk_add_f32 v[86:87], v[86:87], 1.0 op_sel_hi:[1,0]
	v_rcp_f32_e32 v88, v88
	v_rcp_f32_e32 v84, v84
	v_rcp_f32_e32 v89, v89
	v_rcp_f32_e32 v85, v85
	v_rcp_f32_e32 v90, v90
	v_rcp_f32_e32 v86, v86
	v_rcp_f32_e32 v91, v91
	v_rcp_f32_e32 v87, v87
	v_pk_mul_f32 v[80:81], v[80:81], s[98:99] op_sel_hi:[1,0]
	v_pk_mul_f32 v[82:83], v[82:83], s[98:99] op_sel_hi:[1,0]
	v_pk_mul_f32 v[76:77], v[76:77], s[98:99] op_sel_hi:[1,0]
	v_pk_mul_f32 v[78:79], v[78:79], s[98:99] op_sel_hi:[1,0]
	v_exp_f32_e32 v80, v80
	v_exp_f32_e32 v76, v76
	v_exp_f32_e32 v81, v81
	v_exp_f32_e32 v77, v77
	v_exp_f32_e32 v82, v82
	v_exp_f32_e32 v78, v78
	v_exp_f32_e32 v83, v83
	v_exp_f32_e32 v79, v79
	v_pk_add_f32 v[80:81], v[80:81], 1.0 op_sel_hi:[1,0]
	v_pk_add_f32 v[82:83], v[82:83], 1.0 op_sel_hi:[1,0]
	v_pk_add_f32 v[76:77], v[76:77], 1.0 op_sel_hi:[1,0]
	v_pk_add_f32 v[78:79], v[78:79], 1.0 op_sel_hi:[1,0]
	v_rcp_f32_e32 v80, v80
	v_rcp_f32_e32 v76, v76
	v_rcp_f32_e32 v81, v81
	v_rcp_f32_e32 v77, v77
	v_rcp_f32_e32 v82, v82
	v_rcp_f32_e32 v78, v78
	v_rcp_f32_e32 v83, v83
	v_rcp_f32_e32 v79, v79
	v_pk_mul_f32 v[72:73], v[72:73], s[98:99] op_sel_hi:[1,0]
	v_pk_mul_f32 v[74:75], v[74:75], s[98:99] op_sel_hi:[1,0]
	v_pk_mul_f32 v[68:69], v[68:69], s[98:99] op_sel_hi:[1,0]
	v_pk_mul_f32 v[70:71], v[70:71], s[98:99] op_sel_hi:[1,0]
	v_exp_f32_e32 v72, v72
	v_exp_f32_e32 v68, v68
	v_exp_f32_e32 v73, v73
	v_exp_f32_e32 v69, v69
	v_exp_f32_e32 v74, v74
	v_exp_f32_e32 v70, v70
	v_exp_f32_e32 v75, v75
	v_exp_f32_e32 v71, v71
	v_pk_add_f32 v[72:73], v[72:73], 1.0 op_sel_hi:[1,0]
	v_pk_add_f32 v[74:75], v[74:75], 1.0 op_sel_hi:[1,0]
	v_pk_add_f32 v[68:69], v[68:69], 1.0 op_sel_hi:[1,0]
	v_pk_add_f32 v[70:71], v[70:71], 1.0 op_sel_hi:[1,0]
	v_rcp_f32_e32 v72, v72
	v_rcp_f32_e32 v68, v68
	v_rcp_f32_e32 v73, v73
	v_rcp_f32_e32 v69, v69
	v_rcp_f32_e32 v74, v74
	v_rcp_f32_e32 v70, v70
	v_rcp_f32_e32 v75, v75
	v_rcp_f32_e32 v71, v71
	v_pk_mul_f32 v[64:65], v[64:65], s[98:99] op_sel_hi:[1,0]
	v_pk_mul_f32 v[66:67], v[66:67], s[98:99] op_sel_hi:[1,0]
	v_pk_mul_f32 v[60:61], v[60:61], s[98:99] op_sel_hi:[1,0]
	v_pk_mul_f32 v[62:63], v[62:63], s[98:99] op_sel_hi:[1,0]
	v_exp_f32_e32 v64, v64
	v_exp_f32_e32 v60, v60
	v_exp_f32_e32 v65, v65
	v_exp_f32_e32 v61, v61
	v_exp_f32_e32 v66, v66
	v_exp_f32_e32 v62, v62
	v_exp_f32_e32 v67, v67
	v_exp_f32_e32 v63, v63
	v_pk_add_f32 v[64:65], v[64:65], 1.0 op_sel_hi:[1,0]
	v_pk_add_f32 v[66:67], v[66:67], 1.0 op_sel_hi:[1,0]
	v_pk_add_f32 v[60:61], v[60:61], 1.0 op_sel_hi:[1,0]
	v_pk_add_f32 v[62:63], v[62:63], 1.0 op_sel_hi:[1,0]
	v_rcp_f32_e32 v64, v64
	v_rcp_f32_e32 v60, v60
	v_rcp_f32_e32 v65, v65
	v_rcp_f32_e32 v61, v61
	v_rcp_f32_e32 v66, v66
	v_rcp_f32_e32 v62, v62
	v_rcp_f32_e32 v67, v67
	v_rcp_f32_e32 v63, v63
	v_pk_mul_f32 v[56:57], v[56:57], s[98:99] op_sel_hi:[1,0]
	v_pk_mul_f32 v[58:59], v[58:59], s[98:99] op_sel_hi:[1,0]
	v_pk_mul_f32 v[52:53], v[52:53], s[98:99] op_sel_hi:[1,0]
	v_pk_mul_f32 v[54:55], v[54:55], s[98:99] op_sel_hi:[1,0]
	v_exp_f32_e32 v56, v56
	v_exp_f32_e32 v52, v52
	v_exp_f32_e32 v57, v57
	v_exp_f32_e32 v53, v53
	v_exp_f32_e32 v58, v58
	v_exp_f32_e32 v54, v54
	v_exp_f32_e32 v59, v59
	v_exp_f32_e32 v55, v55
	v_pk_add_f32 v[56:57], v[56:57], 1.0 op_sel_hi:[1,0]
	v_pk_add_f32 v[58:59], v[58:59], 1.0 op_sel_hi:[1,0]
	v_pk_add_f32 v[52:53], v[52:53], 1.0 op_sel_hi:[1,0]
	v_pk_add_f32 v[54:55], v[54:55], 1.0 op_sel_hi:[1,0]
	v_rcp_f32_e32 v56, v56
	v_rcp_f32_e32 v52, v52
	v_rcp_f32_e32 v57, v57
	v_rcp_f32_e32 v53, v53
	v_rcp_f32_e32 v58, v58
	v_rcp_f32_e32 v54, v54
	v_rcp_f32_e32 v59, v59
	v_rcp_f32_e32 v55, v55
	v_pk_mul_f32 v[48:49], v[48:49], s[98:99] op_sel_hi:[1,0]
	v_pk_mul_f32 v[50:51], v[50:51], s[98:99] op_sel_hi:[1,0]
	v_pk_mul_f32 v[44:45], v[44:45], s[98:99] op_sel_hi:[1,0]
	v_pk_mul_f32 v[46:47], v[46:47], s[98:99] op_sel_hi:[1,0]
	v_exp_f32_e32 v48, v48
	v_exp_f32_e32 v44, v44
	v_exp_f32_e32 v49, v49
	v_exp_f32_e32 v45, v45
	v_exp_f32_e32 v50, v50
	v_exp_f32_e32 v46, v46
	v_exp_f32_e32 v51, v51
	v_exp_f32_e32 v47, v47
	v_pk_add_f32 v[48:49], v[48:49], 1.0 op_sel_hi:[1,0]
	v_pk_add_f32 v[50:51], v[50:51], 1.0 op_sel_hi:[1,0]
	v_pk_add_f32 v[44:45], v[44:45], 1.0 op_sel_hi:[1,0]
	v_pk_add_f32 v[46:47], v[46:47], 1.0 op_sel_hi:[1,0]
	v_rcp_f32_e32 v48, v48
	v_rcp_f32_e32 v44, v44
; __device__ __forceinline__ float sigmoidf_(float x) { return __builtin_amdgcn_rcpf(1.0f + __expf(-x)); }
; __device__ __forceinline__ f32x4 sig4(const f32x4 v) { return (f32x4){sigmoidf_(v[0]), sigmoidf_(v[1]), sigmoidf_(v[2]), sigmoidf_(v[3])}; }
;     __device__ __forceinline__ void ple_gate(f32x4 (&acc)[2][2][4][2], const GUnit& u, int wr, int wc, int fr, int fq) const {
;     ...
;         for (int ai = 0; ai < 2; ++ai)
; #pragma unroll
;             for (int m = 0; m < 4; ++m)
; #pragma unroll
;                 for (int bj = 0; bj < 2; ++bj) { f32x4 p0, p1; unpk8(pw[ai][m][bj], p0, p1); acc[ai][bj][m][0] = sig4(acc[ai][bj][m][0]) * p0; acc[ai][bj][m][1] = sig4(acc[ai][bj][m][1]) * p1; }
	v_rcp_f32_e32 v49, v49
	v_rcp_f32_e32 v45, v45
	v_rcp_f32_e32 v50, v50
	v_rcp_f32_e32 v46, v46
	v_rcp_f32_e32 v51, v51
	v_rcp_f32_e32 v47, v47
	v_pk_mul_f32 v[40:41], v[40:41], s[98:99] op_sel_hi:[1,0]
	v_pk_mul_f32 v[42:43], v[42:43], s[98:99] op_sel_hi:[1,0]
	v_pk_mul_f32 v[36:37], v[36:37], s[98:99] op_sel_hi:[1,0]
	v_pk_mul_f32 v[38:39], v[38:39], s[98:99] op_sel_hi:[1,0]
	v_exp_f32_e32 v40, v40
	v_exp_f32_e32 v36, v36
	v_exp_f32_e32 v41, v41
	v_exp_f32_e32 v37, v37
	v_exp_f32_e32 v42, v42
	v_exp_f32_e32 v38, v38
	v_exp_f32_e32 v43, v43
	v_exp_f32_e32 v39, v39
	v_pk_add_f32 v[40:41], v[40:41], 1.0 op_sel_hi:[1,0]
	v_pk_add_f32 v[42:43], v[42:43], 1.0 op_sel_hi:[1,0]
	v_pk_add_f32 v[36:37], v[36:37], 1.0 op_sel_hi:[1,0]
	v_pk_add_f32 v[38:39], v[38:39], 1.0 op_sel_hi:[1,0]
	v_rcp_f32_e32 v40, v40
	v_rcp_f32_e32 v36, v36
	v_rcp_f32_e32 v41, v41
	v_rcp_f32_e32 v37, v37
	v_rcp_f32_e32 v42, v42
	v_rcp_f32_e32 v38, v38
	v_rcp_f32_e32 v43, v43
	v_rcp_f32_e32 v39, v39
	v_pk_mul_f32 v[28:29], v[28:29], s[98:99] op_sel_hi:[1,0]
	v_pk_mul_f32 v[30:31], v[30:31], s[98:99] op_sel_hi:[1,0]
	v_pk_mul_f32 v[24:25], v[24:25], s[98:99] op_sel_hi:[1,0]
	v_pk_mul_f32 v[26:27], v[26:27], s[98:99] op_sel_hi:[1,0]
	v_exp_f32_e32 v28, v28
	v_exp_f32_e32 v24, v24
	v_exp_f32_e32 v29, v29
	v_exp_f32_e32 v25, v25
	v_exp_f32_e32 v30, v30
	v_exp_f32_e32 v26, v26
	v_exp_f32_e32 v31, v31
	v_exp_f32_e32 v27, v27
	v_pk_add_f32 v[28:29], v[28:29], 1.0 op_sel_hi:[1,0]
	v_pk_add_f32 v[30:31], v[30:31], 1.0 op_sel_hi:[1,0]
	v_pk_add_f32 v[24:25], v[24:25], 1.0 op_sel_hi:[1,0]
	v_pk_add_f32 v[26:27], v[26:27], 1.0 op_sel_hi:[1,0]
	v_rcp_f32_e32 v28, v28
	v_rcp_f32_e32 v24, v24
	v_rcp_f32_e32 v29, v29
	v_rcp_f32_e32 v25, v25
	v_rcp_f32_e32 v30, v30
	v_rcp_f32_e32 v26, v26
	v_rcp_f32_e32 v31, v31
	v_rcp_f32_e32 v27, v27
	v_pk_mul_f32 v[20:21], v[20:21], s[98:99] op_sel_hi:[1,0]
	v_pk_mul_f32 v[22:23], v[22:23], s[98:99] op_sel_hi:[1,0]
	v_pk_mul_f32 v[16:17], v[16:17], s[98:99] op_sel_hi:[1,0]
	v_pk_mul_f32 v[18:19], v[18:19], s[98:99] op_sel_hi:[1,0]
	v_exp_f32_e32 v20, v20
	v_exp_f32_e32 v16, v16
	v_exp_f32_e32 v21, v21
	v_exp_f32_e32 v17, v17
	v_exp_f32_e32 v22, v22
	v_exp_f32_e32 v18, v18
	v_exp_f32_e32 v23, v23
	v_exp_f32_e32 v19, v19
	v_pk_add_f32 v[20:21], v[20:21], 1.0 op_sel_hi:[1,0]
	v_pk_add_f32 v[22:23], v[22:23], 1.0 op_sel_hi:[1,0]
	v_pk_add_f32 v[16:17], v[16:17], 1.0 op_sel_hi:[1,0]
	v_pk_add_f32 v[18:19], v[18:19], 1.0 op_sel_hi:[1,0]
	v_rcp_f32_e32 v20, v20
	v_rcp_f32_e32 v16, v16
	v_rcp_f32_e32 v21, v21
	v_rcp_f32_e32 v17, v17
	v_rcp_f32_e32 v22, v22
	v_rcp_f32_e32 v18, v18
	v_rcp_f32_e32 v23, v23
	v_rcp_f32_e32 v19, v19
	v_pk_mul_f32 v[12:13], v[12:13], s[98:99] op_sel_hi:[1,0]
	v_pk_mul_f32 v[14:15], v[14:15], s[98:99] op_sel_hi:[1,0]
	v_pk_mul_f32 v[8:9], v[8:9], s[98:99] op_sel_hi:[1,0]
	v_pk_mul_f32 v[10:11], v[10:11], s[98:99] op_sel_hi:[1,0]
	v_exp_f32_e32 v12, v12
	v_exp_f32_e32 v8, v8
	v_exp_f32_e32 v13, v13
	v_exp_f32_e32 v9, v9
	v_exp_f32_e32 v14, v14
	v_exp_f32_e32 v10, v10
	v_exp_f32_e32 v15, v15
	v_exp_f32_e32 v11, v11
	v_pk_add_f32 v[12:13], v[12:13], 1.0 op_sel_hi:[1,0]
	v_pk_add_f32 v[14:15], v[14:15], 1.0 op_sel_hi:[1,0]
	v_pk_add_f32 v[8:9], v[8:9], 1.0 op_sel_hi:[1,0]
	v_pk_add_f32 v[10:11], v[10:11], 1.0 op_sel_hi:[1,0]
	v_rcp_f32_e32 v12, v12
	v_rcp_f32_e32 v8, v8
	v_rcp_f32_e32 v13, v13
	v_rcp_f32_e32 v9, v9
	v_rcp_f32_e32 v14, v14
	v_rcp_f32_e32 v10, v10
	v_rcp_f32_e32 v15, v15
	v_rcp_f32_e32 v11, v11
	v_pk_mul_f32 v[4:5], v[4:5], s[98:99] op_sel_hi:[1,0]
	v_pk_mul_f32 v[6:7], v[6:7], s[98:99] op_sel_hi:[1,0]
	v_pk_mul_f32 v[0:1], v[0:1], s[98:99] op_sel_hi:[1,0]
	v_pk_mul_f32 v[2:3], v[2:3], s[98:99] op_sel_hi:[1,0]
	v_exp_f32_e32 v4, v4
	v_exp_f32_e32 v0, v0
	v_exp_f32_e32 v5, v5
	v_exp_f32_e32 v1, v1
	v_exp_f32_e32 v6, v6
	v_exp_f32_e32 v2, v2
	v_exp_f32_e32 v7, v7
	v_exp_f32_e32 v3, v3
	v_pk_add_f32 v[4:5], v[4:5], 1.0 op_sel_hi:[1,0]
	v_pk_add_f32 v[6:7], v[6:7], 1.0 op_sel_hi:[1,0]
	v_pk_add_f32 v[0:1], v[0:1], 1.0 op_sel_hi:[1,0]
	v_pk_add_f32 v[2:3], v[2:3], 1.0 op_sel_hi:[1,0]
	v_rcp_f32_e32 v4, v4
	v_rcp_f32_e32 v0, v0
	v_rcp_f32_e32 v5, v5
	v_rcp_f32_e32 v1, v1
	v_rcp_f32_e32 v6, v6
	v_rcp_f32_e32 v2, v2
	v_rcp_f32_e32 v7, v7
	v_rcp_f32_e32 v3, v3
	s_waitcnt vmcnt(15)
	v_cvt_f32_f16_e32 v194, v136
	v_cvt_f32_f16_sdwa v195, v136 dst_sel:DWORD dst_unused:UNUSED_PAD src0_sel:WORD_1
	s_nop 0
	v_pk_mul_f32 v[128:129], v[128:129], v[194:195]
	v_cvt_f32_f16_e32 v212, v137
	v_cvt_f32_f16_sdwa v213, v137 dst_sel:DWORD dst_unused:UNUSED_PAD src0_sel:WORD_1
	s_nop 0
	v_pk_mul_f32 v[130:131], v[130:131], v[212:213]
	v_cvt_f32_f16_e32 v194, v138
	v_cvt_f32_f16_sdwa v195, v138 dst_sel:DWORD dst_unused:UNUSED_PAD src0_sel:WORD_1
	s_nop 0
	v_pk_mul_f32 v[124:125], v[124:125], v[194:195]
	v_cvt_f32_f16_e32 v212, v139
	v_cvt_f32_f16_sdwa v213, v139 dst_sel:DWORD dst_unused:UNUSED_PAD src0_sel:WORD_1
	s_nop 0
	v_pk_mul_f32 v[126:127], v[126:127], v[212:213]
	s_waitcnt vmcnt(14)
	v_cvt_f32_f16_e32 v194, v140
	v_cvt_f32_f16_sdwa v195, v140 dst_sel:DWORD dst_unused:UNUSED_PAD src0_sel:WORD_1
	s_nop 0
	v_pk_mul_f32 v[120:121], v[120:121], v[194:195]
	v_cvt_f32_f16_e32 v212, v141
	v_cvt_f32_f16_sdwa v213, v141 dst_sel:DWORD dst_unused:UNUSED_PAD src0_sel:WORD_1
	s_nop 0
	v_pk_mul_f32 v[122:123], v[122:123], v[212:213]
	v_cvt_f32_f16_e32 v194, v142
	v_cvt_f32_f16_sdwa v195, v142 dst_sel:DWORD dst_unused:UNUSED_PAD src0_sel:WORD_1
	s_nop 0
	v_pk_mul_f32 v[116:117], v[116:117], v[194:195]
	v_cvt_f32_f16_e32 v212, v143
	v_cvt_f32_f16_sdwa v213, v143 dst_sel:DWORD dst_unused:UNUSED_PAD src0_sel:WORD_1
	s_nop 0
	v_pk_mul_f32 v[118:119], v[118:119], v[212:213]
	s_waitcnt vmcnt(13)
; __device__ __forceinline__ f32x4 sig4(const f32x4 v) { return (f32x4){sigmoidf_(v[0]), sigmoidf_(v[1]), sigmoidf_(v[2]), sigmoidf_(v[3])}; }
;     __device__ __forceinline__ void ple_gate(f32x4 (&acc)[2][2][4][2], const GUnit& u, int wr, int wc, int fr, int fq) const {
;     ...
;         for (int ai = 0; ai < 2; ++ai)
; #pragma unroll
;             for (int m = 0; m < 4; ++m)
; #pragma unroll
;                 for (int bj = 0; bj < 2; ++bj) { f32x4 p0, p1; unpk8(pw[ai][m][bj], p0, p1); acc[ai][bj][m][0] = sig4(acc[ai][bj][m][0]) * p0; acc[ai][bj][m][1] = sig4(acc[ai][bj][m][1]) * p1; }
	v_cvt_f32_f16_e32 v194, v144
	v_cvt_f32_f16_sdwa v195, v144 dst_sel:DWORD dst_unused:UNUSED_PAD src0_sel:WORD_1
	s_nop 0
	v_pk_mul_f32 v[112:113], v[112:113], v[194:195]
	v_cvt_f32_f16_e32 v212, v145
	v_cvt_f32_f16_sdwa v213, v145 dst_sel:DWORD dst_unused:UNUSED_PAD src0_sel:WORD_1
	s_nop 0
	v_pk_mul_f32 v[114:115], v[114:115], v[212:213]
	v_cvt_f32_f16_e32 v194, v146
	v_cvt_f32_f16_sdwa v195, v146 dst_sel:DWORD dst_unused:UNUSED_PAD src0_sel:WORD_1
	s_nop 0
	v_pk_mul_f32 v[108:109], v[108:109], v[194:195]
	v_cvt_f32_f16_e32 v212, v147
	v_cvt_f32_f16_sdwa v213, v147 dst_sel:DWORD dst_unused:UNUSED_PAD src0_sel:WORD_1
	s_nop 0
	v_pk_mul_f32 v[110:111], v[110:111], v[212:213]
	s_waitcnt vmcnt(12)
	v_cvt_f32_f16_e32 v194, v148
	v_cvt_f32_f16_sdwa v195, v148 dst_sel:DWORD dst_unused:UNUSED_PAD src0_sel:WORD_1
	s_nop 0
	v_pk_mul_f32 v[104:105], v[104:105], v[194:195]
	v_cvt_f32_f16_e32 v212, v149
	v_cvt_f32_f16_sdwa v213, v149 dst_sel:DWORD dst_unused:UNUSED_PAD src0_sel:WORD_1
	s_nop 0
	v_pk_mul_f32 v[106:107], v[106:107], v[212:213]
	v_cvt_f32_f16_e32 v194, v150
	v_cvt_f32_f16_sdwa v195, v150 dst_sel:DWORD dst_unused:UNUSED_PAD src0_sel:WORD_1
	s_nop 0
	v_pk_mul_f32 v[100:101], v[100:101], v[194:195]
	v_cvt_f32_f16_e32 v212, v151
	v_cvt_f32_f16_sdwa v213, v151 dst_sel:DWORD dst_unused:UNUSED_PAD src0_sel:WORD_1
	s_nop 0
	v_pk_mul_f32 v[102:103], v[102:103], v[212:213]
	s_waitcnt vmcnt(11)
	v_cvt_f32_f16_e32 v194, v152
	v_cvt_f32_f16_sdwa v195, v152 dst_sel:DWORD dst_unused:UNUSED_PAD src0_sel:WORD_1
	s_nop 0
	v_pk_mul_f32 v[96:97], v[96:97], v[194:195]
	v_cvt_f32_f16_e32 v212, v153
	v_cvt_f32_f16_sdwa v213, v153 dst_sel:DWORD dst_unused:UNUSED_PAD src0_sel:WORD_1
	s_nop 0
	v_pk_mul_f32 v[98:99], v[98:99], v[212:213]
	v_cvt_f32_f16_e32 v194, v154
	v_cvt_f32_f16_sdwa v195, v154 dst_sel:DWORD dst_unused:UNUSED_PAD src0_sel:WORD_1
	s_nop 0
	v_pk_mul_f32 v[92:93], v[92:93], v[194:195]
	v_cvt_f32_f16_e32 v212, v155
	v_cvt_f32_f16_sdwa v213, v155 dst_sel:DWORD dst_unused:UNUSED_PAD src0_sel:WORD_1
	s_nop 0
	v_pk_mul_f32 v[94:95], v[94:95], v[212:213]
	s_waitcnt vmcnt(10)
	v_cvt_f32_f16_e32 v194, v156
	v_cvt_f32_f16_sdwa v195, v156 dst_sel:DWORD dst_unused:UNUSED_PAD src0_sel:WORD_1
	s_nop 0
	v_pk_mul_f32 v[88:89], v[88:89], v[194:195]
	v_cvt_f32_f16_e32 v212, v157
	v_cvt_f32_f16_sdwa v213, v157 dst_sel:DWORD dst_unused:UNUSED_PAD src0_sel:WORD_1
	s_nop 0
	v_pk_mul_f32 v[90:91], v[90:91], v[212:213]
	v_cvt_f32_f16_e32 v194, v158
	v_cvt_f32_f16_sdwa v195, v158 dst_sel:DWORD dst_unused:UNUSED_PAD src0_sel:WORD_1
	s_nop 0
	v_pk_mul_f32 v[84:85], v[84:85], v[194:195]
	v_cvt_f32_f16_e32 v212, v159
	v_cvt_f32_f16_sdwa v213, v159 dst_sel:DWORD dst_unused:UNUSED_PAD src0_sel:WORD_1
	s_nop 0
	v_pk_mul_f32 v[86:87], v[86:87], v[212:213]
	s_waitcnt vmcnt(9)
	v_cvt_f32_f16_e32 v194, v160
	v_cvt_f32_f16_sdwa v195, v160 dst_sel:DWORD dst_unused:UNUSED_PAD src0_sel:WORD_1
	s_nop 0
	v_pk_mul_f32 v[80:81], v[80:81], v[194:195]
	v_cvt_f32_f16_e32 v212, v161
	v_cvt_f32_f16_sdwa v213, v161 dst_sel:DWORD dst_unused:UNUSED_PAD src0_sel:WORD_1
	s_nop 0
	v_pk_mul_f32 v[82:83], v[82:83], v[212:213]
	v_cvt_f32_f16_e32 v194, v162
	v_cvt_f32_f16_sdwa v195, v162 dst_sel:DWORD dst_unused:UNUSED_PAD src0_sel:WORD_1
	s_nop 0
	v_pk_mul_f32 v[76:77], v[76:77], v[194:195]
	v_cvt_f32_f16_e32 v212, v163
	v_cvt_f32_f16_sdwa v213, v163 dst_sel:DWORD dst_unused:UNUSED_PAD src0_sel:WORD_1
	s_nop 0
	v_pk_mul_f32 v[78:79], v[78:79], v[212:213]
	s_waitcnt vmcnt(8)
	v_cvt_f32_f16_e32 v194, v164
	v_cvt_f32_f16_sdwa v195, v164 dst_sel:DWORD dst_unused:UNUSED_PAD src0_sel:WORD_1
	s_nop 0
	v_pk_mul_f32 v[72:73], v[72:73], v[194:195]
	v_cvt_f32_f16_e32 v212, v165
	v_cvt_f32_f16_sdwa v213, v165 dst_sel:DWORD dst_unused:UNUSED_PAD src0_sel:WORD_1
	s_nop 0
	v_pk_mul_f32 v[74:75], v[74:75], v[212:213]
	v_cvt_f32_f16_e32 v194, v166
	v_cvt_f32_f16_sdwa v195, v166 dst_sel:DWORD dst_unused:UNUSED_PAD src0_sel:WORD_1
	s_nop 0
	v_pk_mul_f32 v[68:69], v[68:69], v[194:195]
	v_cvt_f32_f16_e32 v212, v167
	v_cvt_f32_f16_sdwa v213, v167 dst_sel:DWORD dst_unused:UNUSED_PAD src0_sel:WORD_1
	s_nop 0
	v_pk_mul_f32 v[70:71], v[70:71], v[212:213]
	s_waitcnt vmcnt(7)
	v_cvt_f32_f16_e32 v194, v168
	v_cvt_f32_f16_sdwa v195, v168 dst_sel:DWORD dst_unused:UNUSED_PAD src0_sel:WORD_1
	s_nop 0
	v_pk_mul_f32 v[64:65], v[64:65], v[194:195]
	v_cvt_f32_f16_e32 v212, v169
	v_cvt_f32_f16_sdwa v213, v169 dst_sel:DWORD dst_unused:UNUSED_PAD src0_sel:WORD_1
	s_nop 0
	v_pk_mul_f32 v[66:67], v[66:67], v[212:213]
	v_cvt_f32_f16_e32 v194, v170
	v_cvt_f32_f16_sdwa v195, v170 dst_sel:DWORD dst_unused:UNUSED_PAD src0_sel:WORD_1
	s_nop 0
	v_pk_mul_f32 v[60:61], v[60:61], v[194:195]
	v_cvt_f32_f16_e32 v212, v171
	v_cvt_f32_f16_sdwa v213, v171 dst_sel:DWORD dst_unused:UNUSED_PAD src0_sel:WORD_1
	s_nop 0
	v_pk_mul_f32 v[62:63], v[62:63], v[212:213]
	s_waitcnt vmcnt(6)
; __device__ __forceinline__ f32x4 sig4(const f32x4 v) { return (f32x4){sigmoidf_(v[0]), sigmoidf_(v[1]), sigmoidf_(v[2]), sigmoidf_(v[3])}; }
;     __device__ __forceinline__ void ple_gate(f32x4 (&acc)[2][2][4][2], const GUnit& u, int wr, int wc, int fr, int fq) const {
;     ...
;         for (int ai = 0; ai < 2; ++ai)
; #pragma unroll
;             for (int m = 0; m < 4; ++m)
; #pragma unroll
;                 for (int bj = 0; bj < 2; ++bj) { f32x4 p0, p1; unpk8(pw[ai][m][bj], p0, p1); acc[ai][bj][m][0] = sig4(acc[ai][bj][m][0]) * p0; acc[ai][bj][m][1] = sig4(acc[ai][bj][m][1]) * p1; }
	v_cvt_f32_f16_e32 v194, v172
	v_cvt_f32_f16_sdwa v195, v172 dst_sel:DWORD dst_unused:UNUSED_PAD src0_sel:WORD_1
	s_nop 0
	v_pk_mul_f32 v[56:57], v[56:57], v[194:195]
	v_cvt_f32_f16_e32 v212, v173
	v_cvt_f32_f16_sdwa v213, v173 dst_sel:DWORD dst_unused:UNUSED_PAD src0_sel:WORD_1
	s_nop 0
	v_pk_mul_f32 v[58:59], v[58:59], v[212:213]
	v_cvt_f32_f16_e32 v194, v174
	v_cvt_f32_f16_sdwa v195, v174 dst_sel:DWORD dst_unused:UNUSED_PAD src0_sel:WORD_1
	s_nop 0
	v_pk_mul_f32 v[52:53], v[52:53], v[194:195]
	v_cvt_f32_f16_e32 v212, v175
	v_cvt_f32_f16_sdwa v213, v175 dst_sel:DWORD dst_unused:UNUSED_PAD src0_sel:WORD_1
	s_nop 0
	v_pk_mul_f32 v[54:55], v[54:55], v[212:213]
	s_waitcnt vmcnt(5)
	v_cvt_f32_f16_e32 v194, v176
	v_cvt_f32_f16_sdwa v195, v176 dst_sel:DWORD dst_unused:UNUSED_PAD src0_sel:WORD_1
	s_nop 0
	v_pk_mul_f32 v[48:49], v[48:49], v[194:195]
	v_cvt_f32_f16_e32 v212, v177
	v_cvt_f32_f16_sdwa v213, v177 dst_sel:DWORD dst_unused:UNUSED_PAD src0_sel:WORD_1
	s_nop 0
	v_pk_mul_f32 v[50:51], v[50:51], v[212:213]
	v_cvt_f32_f16_e32 v194, v178
	v_cvt_f32_f16_sdwa v195, v178 dst_sel:DWORD dst_unused:UNUSED_PAD src0_sel:WORD_1
	s_nop 0
	v_pk_mul_f32 v[44:45], v[44:45], v[194:195]
	v_cvt_f32_f16_e32 v212, v179
	v_cvt_f32_f16_sdwa v213, v179 dst_sel:DWORD dst_unused:UNUSED_PAD src0_sel:WORD_1
	s_nop 0
	v_pk_mul_f32 v[46:47], v[46:47], v[212:213]
	s_waitcnt vmcnt(4)
	v_cvt_f32_f16_e32 v194, v180
	v_cvt_f32_f16_sdwa v195, v180 dst_sel:DWORD dst_unused:UNUSED_PAD src0_sel:WORD_1
	s_nop 0
	v_pk_mul_f32 v[40:41], v[40:41], v[194:195]
	v_cvt_f32_f16_e32 v212, v181
	v_cvt_f32_f16_sdwa v213, v181 dst_sel:DWORD dst_unused:UNUSED_PAD src0_sel:WORD_1
	s_nop 0
	v_pk_mul_f32 v[42:43], v[42:43], v[212:213]
	v_cvt_f32_f16_e32 v194, v182
	v_cvt_f32_f16_sdwa v195, v182 dst_sel:DWORD dst_unused:UNUSED_PAD src0_sel:WORD_1
	s_nop 0
	v_pk_mul_f32 v[36:37], v[36:37], v[194:195]
	v_cvt_f32_f16_e32 v212, v183
	v_cvt_f32_f16_sdwa v213, v183 dst_sel:DWORD dst_unused:UNUSED_PAD src0_sel:WORD_1
	s_nop 0
	v_pk_mul_f32 v[38:39], v[38:39], v[212:213]
	s_waitcnt vmcnt(3)
	v_cvt_f32_f16_e32 v194, v190
	v_cvt_f32_f16_sdwa v195, v190 dst_sel:DWORD dst_unused:UNUSED_PAD src0_sel:WORD_1
	s_nop 0
	v_pk_mul_f32 v[28:29], v[28:29], v[194:195]
	v_cvt_f32_f16_e32 v212, v191
	v_cvt_f32_f16_sdwa v213, v191 dst_sel:DWORD dst_unused:UNUSED_PAD src0_sel:WORD_1
	s_nop 0
	v_pk_mul_f32 v[30:31], v[30:31], v[212:213]
	v_cvt_f32_f16_e32 v194, v192
	v_cvt_f32_f16_sdwa v195, v192 dst_sel:DWORD dst_unused:UNUSED_PAD src0_sel:WORD_1
	s_nop 0
	v_pk_mul_f32 v[24:25], v[24:25], v[194:195]
	v_cvt_f32_f16_e32 v212, v193
	v_cvt_f32_f16_sdwa v213, v193 dst_sel:DWORD dst_unused:UNUSED_PAD src0_sel:WORD_1
	s_nop 0
	v_pk_mul_f32 v[26:27], v[26:27], v[212:213]
	s_waitcnt vmcnt(2)
	v_cvt_f32_f16_e32 v194, v198
	v_cvt_f32_f16_sdwa v195, v198 dst_sel:DWORD dst_unused:UNUSED_PAD src0_sel:WORD_1
	s_nop 0
	v_pk_mul_f32 v[20:21], v[20:21], v[194:195]
	v_cvt_f32_f16_e32 v212, v199
	v_cvt_f32_f16_sdwa v213, v199 dst_sel:DWORD dst_unused:UNUSED_PAD src0_sel:WORD_1
	s_nop 0
	v_pk_mul_f32 v[22:23], v[22:23], v[212:213]
	v_cvt_f32_f16_e32 v194, v200
	v_cvt_f32_f16_sdwa v195, v200 dst_sel:DWORD dst_unused:UNUSED_PAD src0_sel:WORD_1
	s_nop 0
	v_pk_mul_f32 v[16:17], v[16:17], v[194:195]
	v_cvt_f32_f16_e32 v212, v201
	v_cvt_f32_f16_sdwa v213, v201 dst_sel:DWORD dst_unused:UNUSED_PAD src0_sel:WORD_1
	s_nop 0
	v_pk_mul_f32 v[18:19], v[18:19], v[212:213]
	s_waitcnt vmcnt(1)
	v_cvt_f32_f16_e32 v194, v204
	v_cvt_f32_f16_sdwa v195, v204 dst_sel:DWORD dst_unused:UNUSED_PAD src0_sel:WORD_1
	s_nop 0
	v_pk_mul_f32 v[12:13], v[12:13], v[194:195]
	v_cvt_f32_f16_e32 v212, v205
	v_cvt_f32_f16_sdwa v213, v205 dst_sel:DWORD dst_unused:UNUSED_PAD src0_sel:WORD_1
	s_nop 0
	v_pk_mul_f32 v[14:15], v[14:15], v[212:213]
	v_cvt_f32_f16_e32 v194, v206
	v_cvt_f32_f16_sdwa v195, v206 dst_sel:DWORD dst_unused:UNUSED_PAD src0_sel:WORD_1
	s_nop 0
	v_pk_mul_f32 v[8:9], v[8:9], v[194:195]
	v_cvt_f32_f16_e32 v212, v207
	v_cvt_f32_f16_sdwa v213, v207 dst_sel:DWORD dst_unused:UNUSED_PAD src0_sel:WORD_1
	s_nop 0
	v_pk_mul_f32 v[10:11], v[10:11], v[212:213]
	s_waitcnt vmcnt(0)
	v_cvt_f32_f16_e32 v194, v208
	v_cvt_f32_f16_sdwa v195, v208 dst_sel:DWORD dst_unused:UNUSED_PAD src0_sel:WORD_1
	s_nop 0
	v_pk_mul_f32 v[4:5], v[4:5], v[194:195]
	v_cvt_f32_f16_e32 v212, v209
	v_cvt_f32_f16_sdwa v213, v209 dst_sel:DWORD dst_unused:UNUSED_PAD src0_sel:WORD_1
	s_nop 0
	v_pk_mul_f32 v[6:7], v[6:7], v[212:213]
	v_cvt_f32_f16_e32 v194, v210
	v_cvt_f32_f16_sdwa v195, v210 dst_sel:DWORD dst_unused:UNUSED_PAD src0_sel:WORD_1
	s_nop 0
	v_pk_mul_f32 v[0:1], v[0:1], v[194:195]
	v_cvt_f32_f16_e32 v212, v211
	v_cvt_f32_f16_sdwa v213, v211 dst_sel:DWORD dst_unused:UNUSED_PAD src0_sel:WORD_1
	s_nop 0
	v_pk_mul_f32 v[2:3], v[2:3], v[212:213]
	s_andn2_b64 vcc, exec, s[30:31]
	s_cbranch_vccz .LBB0_222
